# v85 + FFN-up K-loop: the remaining 8 VGPR-address LDS-DMA loads per iteration converted to SGPR base + lane offset (t+3 pieces via s[98:99]/s[100:101] = base + 0x80)
# baseline (speedup 1.0000x reference)
; #define PG8_STAGE(bufoff, gbase, voff) do { _Pragma("unroll") for (int _i = 0; _i < 2; ++_i) \
;         __builtin_amdgcn_global_load_lds((const unsigned*)((const char*)(gbase) + (voff)[_i]), (PG8_LAS unsigned*)(lds + (bufoff) + ldsw + _i * 8192), 16, 0, 0); } while (0)
; #define PG8_LDA(dst, b, h) do { _Pragma("unroll") for (int m = 0; m < 4; ++m) _Pragma("unroll") for (int k = 0; k < 2; ++k) dst[m][k] = *(const PG8_LAS bf16x8*)(lds + PG8_SA(b, h) + aoff + m * 2048 + k * 1024); } while (0)
; #define PG8_LDB(dst, b, h) do { _Pragma("unroll") for (int n = 0; n < 2; ++n) _Pragma("unroll") for (int k = 0; k < 2; ++k) dst[n][k] = *(const PG8_LAS bf16x8*)(lds + PG8_SB(b, h) + boff + n * 2048 + k * 1024); } while (0)
; #define PG8_MMA(ai, bj, At, Bt) do { __builtin_amdgcn_s_setprio(1); _Pragma("unroll") for (int m = 0; m < 4; ++m) _Pragma("unroll") for (int n = 0; n < 2; ++n) _Pragma("unroll") for (int k = 0; k < 2; ++k) \
;         acc[ai][bj][m][n] = mma16<Epi::I8>(Bt[n][k], At[m][k], acc[ai][bj][m][n]); __builtin_amdgcn_s_setprio(0); } while (0)
; #define PG8_WAIT_V(n) asm volatile("s_waitcnt vmcnt(" #n ")" ::: "memory")
; #define PG8_WAIT_L(n) asm volatile("s_waitcnt lgkmcnt(" #n ")" ::: "memory")
; #define PG8_BAR __builtin_amdgcn_s_barrier()
; template <class Epi, class Sched, bool ALIGN_EPI = false, bool SP2 = false>
; __device__ __forceinline__ void gemm_phase(PG8_LAS unsigned char* lds, const Gemm g, const Sched& S, const Epi& E) {
;     ...
;             const bool last = (t == nt - 2);
;             const char* a1 = cA + (size_t)(t + 1) * kstep;
;             const char* a2 = last ? nA : cA + (size_t)(t + 2) * kstep; const char* b2 = last ? nB : cB + (size_t)(t + 2) * kstep;
;             const char* a3 = a2 + kstep; const char* b3 = b2 + kstep;
;             if (last && has_next) S.a_ready(nxt);
;             if constexpr (SP2) {
;             PG8_LDB(B0, 0, 0); PG8_LDB(B1, 0, 1); PG8_SCHED; PG8_LDA(At, 0, 0); PG8_STAGE(PG8_SA(1, 1), a1 + hstep, voffA);
;             PG8_WAIT_V(8); PG8_WAIT_L(0); PG8_BAR; PG8_MMA(0, 0, At, B0); PG8_MMA(0, 1, At, B1); PG8_BAR; PG8_SCHED;
;             PG8_LDA(At, 0, 1); PG8_STAGE(PG8_SB(0, 0), b2, voffB); PG8_STAGE(PG8_SB(0, 1), b2 + hstep, voffB); PG8_STAGE(PG8_SA(0, 0), a2, voffA);
;             PG8_WAIT_V(8); PG8_WAIT_L(0); PG8_BAR; PG8_MMA(1, 0, At, B0); PG8_MMA(1, 1, At, B1); PG8_BAR; PG8_SCHED;
.Lpeel80:
	s_add_u32 s8, s0, 0x100
	s_addc_u32 s9, s1, 0
	s_add_i32 vcc_hi, 0, 0x10000
	s_cmp_eq_u32 vcc_lo, 12
	s_cselect_b32 s13, s66, s9
	s_cselect_b32 s12, s67, s8
	s_cselect_b32 s7, s82, s97
	s_cselect_b32 s6, s83, s96
	s_add_i32 s4, 0, 0x14000
	v_add_u32_e32 v38, vcc_hi, v242
	v_add_u32_e32 v158, s4, v242
	ds_read_b128 v[18:21], v38
	ds_read_b128 v[22:25], v38 offset:1024
	ds_read_b128 v[34:37], v38 offset:2048
	ds_read_b128 v[38:41], v38 offset:3072
	ds_read_b128 v[130:133], v158
	ds_read_b128 v[134:137], v158 offset:1024
	ds_read_b128 v[154:157], v158 offset:2048
	ds_read_b128 v[158:161], v158 offset:3072
	s_add_i32 m0, s11, 0xc000
	ds_read_b128 v[162:165], v243
	ds_read_b128 v[166:169], v243 offset:1024
	ds_read_b128 v[170:173], v243 offset:2048
	ds_read_b128 v[174:177], v243 offset:3072
	ds_read_b128 v[178:181], v243 offset:4096
	ds_read_b128 v[182:185], v243 offset:5120
	ds_read_b128 v[186:189], v243 offset:6144
	ds_read_b128 v[190:193], v243 offset:7168
	global_load_lds_dwordx4 v216, s[0:1]
	s_add_i32 m0, s11, 0xe000
	s_nop 0
	global_load_lds_dwordx4 v218, s[0:1]
	s_waitcnt vmcnt(8)
	s_waitcnt lgkmcnt(0)
	s_barrier
	s_waitcnt lgkmcnt(0)
	v_mfma_i32_16x16x64_i8 v[150:153], v[18:21], v[162:165], 0
	v_mfma_i32_16x16x64_i8 v[146:149], v[34:37], v[162:165], 0
	v_mfma_i32_16x16x64_i8 v[110:113], v[34:37], v[170:173], 0
	v_mfma_i32_16x16x64_i8 v[118:121], v[18:21], v[170:173], 0
	v_mfma_i32_16x16x64_i8 v[54:57], v[18:21], v[178:181], 0
	v_mfma_i32_16x16x64_i8 v[30:33], v[34:37], v[178:181], 0
	v_mfma_i32_16x16x64_i8 v[58:61], v[34:37], v[186:189], 0
	v_mfma_i32_16x16x64_i8 v[94:97], v[18:21], v[186:189], 0
	v_mfma_i32_16x16x64_i8 v[150:153], v[22:25], v[166:169], v[150:153]
	v_mfma_i32_16x16x64_i8 v[146:149], v[38:41], v[166:169], v[146:149]
	v_mfma_i32_16x16x64_i8 v[110:113], v[38:41], v[174:177], v[110:113]
	v_mfma_i32_16x16x64_i8 v[118:121], v[22:25], v[174:177], v[118:121]
	v_mfma_i32_16x16x64_i8 v[54:57], v[22:25], v[182:185], v[54:57]
	v_mfma_i32_16x16x64_i8 v[30:33], v[38:41], v[182:185], v[30:33]
	v_mfma_i32_16x16x64_i8 v[58:61], v[38:41], v[190:193], v[58:61]
	v_mfma_i32_16x16x64_i8 v[94:97], v[22:25], v[190:193], v[94:97]
	v_mfma_i32_16x16x64_i8 v[142:145], v[130:133], v[162:165], 0
	v_mfma_i32_16x16x64_i8 v[138:141], v[154:157], v[162:165], 0
	v_mfma_i32_16x16x64_i8 v[98:101], v[154:157], v[170:173], 0
	v_mfma_i32_16x16x64_i8 v[102:105], v[130:133], v[170:173], 0
	v_mfma_i32_16x16x64_i8 v[42:45], v[130:133], v[178:181], 0
	v_mfma_i32_16x16x64_i8 v[26:29], v[154:157], v[178:181], 0
	v_mfma_i32_16x16x64_i8 v[62:65], v[154:157], v[186:189], 0
	v_mfma_i32_16x16x64_i8 v[78:81], v[130:133], v[186:189], 0
	v_mfma_i32_16x16x64_i8 v[142:145], v[134:137], v[166:169], v[142:145]
	v_mfma_i32_16x16x64_i8 v[138:141], v[158:161], v[166:169], v[138:141]
	v_mfma_i32_16x16x64_i8 v[98:101], v[158:161], v[174:177], v[98:101]
	v_mfma_i32_16x16x64_i8 v[102:105], v[134:137], v[174:177], v[102:105]
	v_mfma_i32_16x16x64_i8 v[42:45], v[134:137], v[182:185], v[42:45]
	v_mfma_i32_16x16x64_i8 v[26:29], v[158:161], v[182:185], v[26:29]
	v_mfma_i32_16x16x64_i8 v[62:65], v[158:161], v[190:193], v[62:65]
	v_mfma_i32_16x16x64_i8 v[78:81], v[134:137], v[190:193], v[78:81]
	s_barrier
	s_add_i32 s0, vcc_hi, s69
	s_mov_b32 m0, s0
	ds_read_b128 v[162:165], v243 offset:16384
	ds_read_b128 v[166:169], v243 offset:17408
	ds_read_b128 v[170:173], v243 offset:18432
	ds_read_b128 v[174:177], v243 offset:19456
	ds_read_b128 v[178:181], v243 offset:20480
	ds_read_b128 v[182:185], v243 offset:21504
	ds_read_b128 v[186:189], v243 offset:22528
	ds_read_b128 v[190:193], v243 offset:23552
	global_load_lds_dwordx4 v0, s[6:7]
	s_add_i32 m0, s0, 0x2000
	s_add_u32 s0, s6, 0x40000
	s_addc_u32 s1, s7, 0
	s_add_i32 s4, s4, s69
	global_load_lds_dwordx4 v214, s[6:7]
	s_mov_b32 m0, s4
	s_nop 0
	global_load_lds_dwordx4 v0, s[0:1]
	s_add_i32 m0, s4, 0x2000
	s_nop 0
	global_load_lds_dwordx4 v214, s[0:1]
	s_mov_b32 m0, s11
	s_nop 0
	global_load_lds_dwordx4 v210, s[12:13]
	s_mov_b32 m0, s71
	s_nop 0
	global_load_lds_dwordx4 v212, s[12:13]
	s_waitcnt vmcnt(8)
	s_waitcnt lgkmcnt(0)
	s_barrier
	s_waitcnt lgkmcnt(0)
	v_mfma_i32_16x16x64_i8 v[106:109], v[18:21], v[162:165], 0
	v_mfma_i32_16x16x64_i8 v[46:49], v[34:37], v[162:165], 0
	v_mfma_i32_16x16x64_i8 v[6:9], v[34:37], v[170:173], 0
	v_mfma_i32_16x16x64_i8 v[14:17], v[18:21], v[170:173], 0
	v_mfma_i32_16x16x64_i8 v[90:93], v[18:21], v[178:181], 0
	v_mfma_i32_16x16x64_i8 v[86:89], v[34:37], v[178:181], 0
	v_mfma_i32_16x16x64_i8 v[18:21], v[18:21], v[186:189], 0
	v_mfma_i32_16x16x64_i8 v[106:109], v[22:25], v[166:169], v[106:109]
	v_mfma_i32_16x16x64_i8 v[46:49], v[38:41], v[166:169], v[46:49]
	v_mfma_i32_16x16x64_i8 v[6:9], v[38:41], v[174:177], v[6:9]
	v_mfma_i32_16x16x64_i8 v[14:17], v[22:25], v[174:177], v[14:17]
	v_mfma_i32_16x16x64_i8 v[90:93], v[22:25], v[182:185], v[90:93]
	v_mfma_i32_16x16x64_i8 v[86:89], v[38:41], v[182:185], v[86:89]
	v_mfma_i32_16x16x64_i8 v[18:21], v[22:25], v[190:193], v[18:21]
	v_mfma_i32_16x16x64_i8 v[22:25], v[34:37], v[186:189], 0
	v_mfma_i32_16x16x64_i8 v[22:25], v[38:41], v[190:193], v[22:25]
	v_mfma_i32_16x16x64_i8 v[38:41], v[154:157], v[162:165], 0
	v_mfma_i32_16x16x64_i8 v[2:5], v[154:157], v[170:173], 0
	v_mfma_i32_16x16x64_i8 v[10:13], v[130:133], v[170:173], 0
	v_mfma_i32_16x16x64_i8 v[50:53], v[130:133], v[178:181], 0
	v_mfma_i32_16x16x64_i8 v[34:37], v[130:133], v[162:165], 0
	v_mfma_i32_16x16x64_i8 v[82:85], v[134:137], v[182:185], v[50:53]
	v_mfma_i32_16x16x64_i8 v[50:53], v[154:157], v[178:181], 0
	v_mfma_i32_16x16x64_i8 v[2:5], v[158:161], v[174:177], v[2:5]
	v_mfma_i32_16x16x64_i8 v[10:13], v[134:137], v[174:177], v[10:13]
	v_mfma_i32_16x16x64_i8 v[38:41], v[158:161], v[166:169], v[38:41]
	v_mfma_i32_16x16x64_i8 v[34:37], v[134:137], v[166:169], v[34:37]
	v_mfma_i32_16x16x64_i8 v[74:77], v[158:161], v[182:185], v[50:53]
	v_mfma_i32_16x16x64_i8 v[50:53], v[130:133], v[186:189], 0
	v_mfma_i32_16x16x64_i8 v[122:125], v[134:137], v[190:193], v[50:53]
	v_mfma_i32_16x16x64_i8 v[50:53], v[154:157], v[186:189], 0
	v_mfma_i32_16x16x64_i8 v[70:73], v[158:161], v[190:193], v[50:53]
	s_barrier
; #define PG8_STAGE(bufoff, gbase, voff) do { _Pragma("unroll") for (int _i = 0; _i < 2; ++_i) \
;         __builtin_amdgcn_global_load_lds((const unsigned*)((const char*)(gbase) + (voff)[_i]), (PG8_LAS unsigned*)(lds + (bufoff) + ldsw + _i * 8192), 16, 0, 0); } while (0)
; #define PG8_LDA(dst, b, h) do { _Pragma("unroll") for (int m = 0; m < 4; ++m) _Pragma("unroll") for (int k = 0; k < 2; ++k) dst[m][k] = *(const PG8_LAS bf16x8*)(lds + PG8_SA(b, h) + aoff + m * 2048 + k * 1024); } while (0)
; #define PG8_LDB(dst, b, h) do { _Pragma("unroll") for (int n = 0; n < 2; ++n) _Pragma("unroll") for (int k = 0; k < 2; ++k) dst[n][k] = *(const PG8_LAS bf16x8*)(lds + PG8_SB(b, h) + boff + n * 2048 + k * 1024); } while (0)
; #define PG8_MMA(ai, bj, At, Bt) do { __builtin_amdgcn_s_setprio(1); _Pragma("unroll") for (int m = 0; m < 4; ++m) _Pragma("unroll") for (int n = 0; n < 2; ++n) _Pragma("unroll") for (int k = 0; k < 2; ++k) \
;         acc[ai][bj][m][n] = mma16<Epi::I8>(Bt[n][k], At[m][k], acc[ai][bj][m][n]); __builtin_amdgcn_s_setprio(0); } while (0)
; #define PG8_WAIT_V(n) asm volatile("s_waitcnt vmcnt(" #n ")" ::: "memory")
; #define PG8_WAIT_L(n) asm volatile("s_waitcnt lgkmcnt(" #n ")" ::: "memory")
; #define PG8_BAR __builtin_amdgcn_s_barrier()
; #define PG8_SCHED __builtin_amdgcn_sched_barrier(0)
; template <class Epi, class Sched, bool ALIGN_EPI = false, bool SP2 = false>
; __device__ __forceinline__ void gemm_phase(PG8_LAS unsigned char* lds, const Gemm g, const Sched& S, const Epi& E) {
;     ...
;         for (int t = 0; t < nt; t += 2) {
;     ...
;             PG8_LDB(B0, 1, 0); PG8_LDB(B1, 1, 1); PG8_SCHED; PG8_LDA(At, 1, 0); PG8_STAGE(PG8_SA(0, 1), a2 + hstep, voffA);
;             PG8_WAIT_V(8); PG8_WAIT_L(0); PG8_BAR; PG8_MMA(0, 0, At, B0); PG8_MMA(0, 1, At, B1); PG8_BAR; PG8_SCHED;
;             PG8_LDA(At, 1, 1); PG8_STAGE(PG8_SB(1, 0), b3, voffB); PG8_STAGE(PG8_SB(1, 1), b3 + hstep, voffB); PG8_STAGE(PG8_SA(1, 0), a3, voffA);
;             PG8_WAIT_V(8); PG8_WAIT_L(0); PG8_BAR; PG8_MMA(1, 0, At, B0); PG8_MMA(1, 1, At, B1); PG8_BAR; PG8_SCHED;
	s_add_i32 s4, 0, 0x18000
	v_add_u32_e32 v126, s4, v242
	s_add_i32 s5, 0, 0x1c000
	ds_read_b128 v[50:53], v126
	ds_read_b128 v[66:69], v126 offset:1024
	ds_read_b128 v[114:117], v126 offset:2048
	ds_read_b128 v[130:133], v126 offset:3072
	v_add_u32_e32 v126, s5, v242
	ds_read_b128 v[134:137], v126
	ds_read_b128 v[154:157], v126 offset:1024
	ds_read_b128 v[158:161], v126 offset:2048
	ds_read_b128 v[162:165], v126 offset:3072
	s_add_u32 s0, s12, 0x40000
	s_addc_u32 s1, s13, 0
	s_mov_b32 m0, s80
	ds_read_b128 v[126:129], v243 offset:32768
	ds_read_b128 v[166:169], v243 offset:33792
	ds_read_b128 v[170:173], v243 offset:34816
	ds_read_b128 v[174:177], v243 offset:35840
	ds_read_b128 v[178:181], v243 offset:36864
	ds_read_b128 v[182:185], v243 offset:37888
	ds_read_b128 v[186:189], v243 offset:38912
	ds_read_b128 v[190:193], v243 offset:39936
	global_load_lds_dwordx4 v210, s[0:1]
	s_mov_b32 m0, s81
	s_nop 0
	global_load_lds_dwordx4 v212, s[0:1]
	s_waitcnt vmcnt(8)
	s_waitcnt lgkmcnt(0)
	s_barrier
	s_waitcnt lgkmcnt(0)
	v_mfma_i32_16x16x64_i8 v[150:153], v[50:53], v[126:129], v[150:153]
	v_mfma_i32_16x16x64_i8 v[146:149], v[114:117], v[126:129], v[146:149]
	v_mfma_i32_16x16x64_i8 v[110:113], v[114:117], v[170:173], v[110:113]
	v_mfma_i32_16x16x64_i8 v[118:121], v[50:53], v[170:173], v[118:121]
	v_mfma_i32_16x16x64_i8 v[54:57], v[50:53], v[178:181], v[54:57]
	v_mfma_i32_16x16x64_i8 v[30:33], v[114:117], v[178:181], v[30:33]
	v_mfma_i32_16x16x64_i8 v[58:61], v[114:117], v[186:189], v[58:61]
	v_mfma_i32_16x16x64_i8 v[94:97], v[50:53], v[186:189], v[94:97]
	v_mfma_i32_16x16x64_i8 v[150:153], v[66:69], v[166:169], v[150:153]
	v_mfma_i32_16x16x64_i8 v[146:149], v[130:133], v[166:169], v[146:149]
	v_mfma_i32_16x16x64_i8 v[110:113], v[130:133], v[174:177], v[110:113]
	v_mfma_i32_16x16x64_i8 v[118:121], v[66:69], v[174:177], v[118:121]
	v_mfma_i32_16x16x64_i8 v[54:57], v[66:69], v[182:185], v[54:57]
	v_mfma_i32_16x16x64_i8 v[30:33], v[130:133], v[182:185], v[30:33]
	v_mfma_i32_16x16x64_i8 v[58:61], v[130:133], v[190:193], v[58:61]
	v_mfma_i32_16x16x64_i8 v[94:97], v[66:69], v[190:193], v[94:97]
	v_mfma_i32_16x16x64_i8 v[142:145], v[134:137], v[126:129], v[142:145]
	v_mfma_i32_16x16x64_i8 v[126:129], v[158:161], v[126:129], v[138:141]
	v_mfma_i32_16x16x64_i8 v[98:101], v[158:161], v[170:173], v[98:101]
	v_mfma_i32_16x16x64_i8 v[102:105], v[134:137], v[170:173], v[102:105]
	v_mfma_i32_16x16x64_i8 v[42:45], v[134:137], v[178:181], v[42:45]
	v_mfma_i32_16x16x64_i8 v[26:29], v[158:161], v[178:181], v[26:29]
	v_mfma_i32_16x16x64_i8 v[62:65], v[158:161], v[186:189], v[62:65]
	v_mfma_i32_16x16x64_i8 v[78:81], v[134:137], v[186:189], v[78:81]
	v_mfma_i32_16x16x64_i8 v[142:145], v[154:157], v[166:169], v[142:145]
	v_mfma_i32_16x16x64_i8 v[138:141], v[162:165], v[166:169], v[126:129]
	v_mfma_i32_16x16x64_i8 v[98:101], v[162:165], v[174:177], v[98:101]
	v_mfma_i32_16x16x64_i8 v[102:105], v[154:157], v[174:177], v[102:105]
	v_mfma_i32_16x16x64_i8 v[42:45], v[154:157], v[182:185], v[42:45]
	v_mfma_i32_16x16x64_i8 v[26:29], v[162:165], v[182:185], v[26:29]
	v_mfma_i32_16x16x64_i8 v[62:65], v[162:165], v[190:193], v[62:65]
	v_mfma_i32_16x16x64_i8 v[78:81], v[154:157], v[190:193], v[78:81]
	s_barrier
	s_add_u32 s98, s6, 0x80
	s_addc_u32 s99, s7, 0
	s_add_u32 s100, s12, 0x80
	s_addc_u32 s101, s13, 0
	s_add_i32 s0, s4, s69
	s_mov_b32 m0, s0
	ds_read_b128 v[166:169], v243 offset:49152
	ds_read_b128 v[170:173], v243 offset:50176
	ds_read_b128 v[174:177], v243 offset:51200
	ds_read_b128 v[178:181], v243 offset:52224
	ds_read_b128 v[182:185], v243 offset:53248
	ds_read_b128 v[186:189], v243 offset:54272
	ds_read_b128 v[190:193], v243 offset:55296
	ds_read_b128 v[194:197], v243 offset:56320
	global_load_lds_dwordx4 v0, s[98:99]
	s_add_i32 m0, s0, 0x2000
	s_add_u32 s0, s6, 0x40080
	s_addc_u32 s1, s7, 0
	s_add_i32 s4, s5, s69
	global_load_lds_dwordx4 v214, s[98:99]
	s_mov_b32 m0, s4
	s_nop 0
	global_load_lds_dwordx4 v0, s[0:1]
	s_add_i32 m0, s4, 0x2000
	s_nop 0
	global_load_lds_dwordx4 v214, s[0:1]
	s_mov_b32 m0, s84
	s_nop 0
	global_load_lds_dwordx4 v210, s[100:101]
	s_mov_b32 m0, s85
	s_nop 0
	global_load_lds_dwordx4 v212, s[100:101]
	s_waitcnt vmcnt(8)
	s_waitcnt lgkmcnt(0)
	s_barrier
	s_waitcnt lgkmcnt(0)
	v_mfma_i32_16x16x64_i8 v[18:21], v[50:53], v[190:193], v[18:21]
	v_mfma_i32_16x16x64_i8 v[106:109], v[50:53], v[166:169], v[106:109]
	v_mfma_i32_16x16x64_i8 v[46:49], v[114:117], v[166:169], v[46:49]
	v_mfma_i32_16x16x64_i8 v[6:9], v[114:117], v[174:177], v[6:9]
	v_mfma_i32_16x16x64_i8 v[14:17], v[50:53], v[174:177], v[14:17]
	v_mfma_i32_16x16x64_i8 v[90:93], v[50:53], v[182:185], v[90:93]
	v_mfma_i32_16x16x64_i8 v[86:89], v[114:117], v[182:185], v[86:89]
	v_mfma_i32_16x16x64_i8 v[126:129], v[66:69], v[194:197], v[18:21]
	v_mfma_i32_16x16x64_i8 v[106:109], v[66:69], v[170:173], v[106:109]
	v_mfma_i32_16x16x64_i8 v[46:49], v[130:133], v[170:173], v[46:49]
	v_mfma_i32_16x16x64_i8 v[6:9], v[130:133], v[178:181], v[6:9]
	v_mfma_i32_16x16x64_i8 v[14:17], v[66:69], v[178:181], v[14:17]
	v_mfma_i32_16x16x64_i8 v[90:93], v[66:69], v[186:189], v[90:93]
	v_mfma_i32_16x16x64_i8 v[86:89], v[130:133], v[186:189], v[86:89]
	v_mfma_i32_16x16x64_i8 v[18:21], v[114:117], v[190:193], v[22:25]
	v_mfma_i32_16x16x64_i8 v[66:69], v[130:133], v[194:197], v[18:21]
	v_mfma_i32_16x16x64_i8 v[18:21], v[134:137], v[166:169], v[34:37]
	v_mfma_i32_16x16x64_i8 v[10:13], v[134:137], v[174:177], v[10:13]
	v_mfma_i32_16x16x64_i8 v[2:5], v[158:161], v[174:177], v[2:5]
	v_mfma_i32_16x16x64_i8 v[114:117], v[154:157], v[170:173], v[18:21]
	v_mfma_i32_16x16x64_i8 v[18:21], v[158:161], v[166:169], v[38:41]
	v_mfma_i32_16x16x64_i8 v[50:53], v[162:165], v[170:173], v[18:21]
	v_mfma_i32_16x16x64_i8 v[18:21], v[134:137], v[182:185], v[82:85]
	v_mfma_i32_16x16x64_i8 v[10:13], v[154:157], v[178:181], v[10:13]
	v_mfma_i32_16x16x64_i8 v[2:5], v[162:165], v[178:181], v[2:5]
	v_mfma_i32_16x16x64_i8 v[82:85], v[154:157], v[186:189], v[18:21]
	v_mfma_i32_16x16x64_i8 v[18:21], v[158:161], v[182:185], v[74:77]
	v_mfma_i32_16x16x64_i8 v[74:77], v[162:165], v[186:189], v[18:21]
	v_mfma_i32_16x16x64_i8 v[18:21], v[134:137], v[190:193], v[122:125]
	v_mfma_i32_16x16x64_i8 v[122:125], v[154:157], v[194:197], v[18:21]
	v_mfma_i32_16x16x64_i8 v[18:21], v[158:161], v[190:193], v[70:73]
	v_mfma_i32_16x16x64_i8 v[70:73], v[162:165], v[194:197], v[18:21]
	s_barrier
	s_add_i32 vcc_lo, vcc_lo, 2
	s_add_u32 s96, s96, 0x100
	s_addc_u32 s97, s97, 0
	s_cmp_gt_u32 vcc_lo, 13
	s_mov_b64 s[0:1], s[8:9]
	s_cbranch_scc0 .LBB0_80
	s_branch .Lpeelx80
; #define PG8_STAGE(bufoff, gbase, voff) do { _Pragma("unroll") for (int _i = 0; _i < 2; ++_i) \
;         __builtin_amdgcn_global_load_lds((const unsigned*)((const char*)(gbase) + (voff)[_i]), (PG8_LAS unsigned*)(lds + (bufoff) + ldsw + _i * 8192), 16, 0, 0); } while (0)
; #define PG8_LDA(dst, b, h) do { _Pragma("unroll") for (int m = 0; m < 4; ++m) _Pragma("unroll") for (int k = 0; k < 2; ++k) dst[m][k] = *(const PG8_LAS bf16x8*)(lds + PG8_SA(b, h) + aoff + m * 2048 + k * 1024); } while (0)
; #define PG8_LDB(dst, b, h) do { _Pragma("unroll") for (int n = 0; n < 2; ++n) _Pragma("unroll") for (int k = 0; k < 2; ++k) dst[n][k] = *(const PG8_LAS bf16x8*)(lds + PG8_SB(b, h) + boff + n * 2048 + k * 1024); } while (0)
; #define PG8_MMA(ai, bj, At, Bt) do { __builtin_amdgcn_s_setprio(1); _Pragma("unroll") for (int m = 0; m < 4; ++m) _Pragma("unroll") for (int n = 0; n < 2; ++n) _Pragma("unroll") for (int k = 0; k < 2; ++k) \
;         acc[ai][bj][m][n] = mma16<Epi::I8>(Bt[n][k], At[m][k], acc[ai][bj][m][n]); __builtin_amdgcn_s_setprio(0); } while (0)
; #define PG8_WAIT_V(n) asm volatile("s_waitcnt vmcnt(" #n ")" ::: "memory")
; #define PG8_WAIT_L(n) asm volatile("s_waitcnt lgkmcnt(" #n ")" ::: "memory")
; #define PG8_BAR __builtin_amdgcn_s_barrier()
; template <class Epi, class Sched, bool ALIGN_EPI = false, bool SP2 = false>
; __device__ __forceinline__ void gemm_phase(PG8_LAS unsigned char* lds, const Gemm g, const Sched& S, const Epi& E) {
;     ...
;             const bool last = (t == nt - 2);
;             const char* a1 = cA + (size_t)(t + 1) * kstep;
;             const char* a2 = last ? nA : cA + (size_t)(t + 2) * kstep; const char* b2 = last ? nB : cB + (size_t)(t + 2) * kstep;
;             const char* a3 = a2 + kstep; const char* b3 = b2 + kstep;
;             if (last && has_next) S.a_ready(nxt);
;             if constexpr (SP2) {
;             PG8_LDB(B0, 0, 0); PG8_LDB(B1, 0, 1); PG8_SCHED; PG8_LDA(At, 0, 0); PG8_STAGE(PG8_SA(1, 1), a1 + hstep, voffA);
;             PG8_WAIT_V(8); PG8_WAIT_L(0); PG8_BAR; PG8_MMA(0, 0, At, B0); PG8_MMA(0, 1, At, B1); PG8_BAR; PG8_SCHED;
;             PG8_LDA(At, 0, 1); PG8_STAGE(PG8_SB(0, 0), b2, voffB); PG8_STAGE(PG8_SB(0, 1), b2 + hstep, voffB); PG8_STAGE(PG8_SA(0, 0), a2, voffA);
;             PG8_WAIT_V(8); PG8_WAIT_L(0); PG8_BAR; PG8_MMA(1, 0, At, B0); PG8_MMA(1, 1, At, B1); PG8_BAR; PG8_SCHED;
.LBB0_80:
	s_add_u32 s8, s0, 0x100
	s_addc_u32 s9, s1, 0
	s_add_i32 vcc_hi, 0, 0x10000
	s_cmp_eq_u32 vcc_lo, 12
	s_cselect_b32 s13, s66, s9
	s_cselect_b32 s12, s67, s8
	s_cselect_b32 s7, s82, s97
	s_cselect_b32 s6, s83, s96
	s_add_i32 s4, 0, 0x14000
	v_add_u32_e32 v38, vcc_hi, v242
	v_add_u32_e32 v158, s4, v242
	ds_read_b128 v[18:21], v38
	ds_read_b128 v[22:25], v38 offset:1024
	ds_read_b128 v[34:37], v38 offset:2048
	ds_read_b128 v[38:41], v38 offset:3072
	ds_read_b128 v[130:133], v158
	ds_read_b128 v[134:137], v158 offset:1024
	ds_read_b128 v[154:157], v158 offset:2048
	ds_read_b128 v[158:161], v158 offset:3072
	s_add_i32 m0, s11, 0xc000
	ds_read_b128 v[162:165], v243
	ds_read_b128 v[166:169], v243 offset:1024
	ds_read_b128 v[170:173], v243 offset:2048
	ds_read_b128 v[174:177], v243 offset:3072
	ds_read_b128 v[178:181], v243 offset:4096
	ds_read_b128 v[182:185], v243 offset:5120
	ds_read_b128 v[186:189], v243 offset:6144
	ds_read_b128 v[190:193], v243 offset:7168
	global_load_lds_dwordx4 v216, s[0:1]
	s_add_i32 m0, s11, 0xe000
	s_nop 0
	global_load_lds_dwordx4 v218, s[0:1]
	s_waitcnt vmcnt(8)
	s_waitcnt lgkmcnt(0)
	s_barrier
	s_waitcnt lgkmcnt(0)
	v_mfma_i32_16x16x64_i8 v[150:153], v[18:21], v[162:165], v[150:153]
	v_mfma_i32_16x16x64_i8 v[146:149], v[34:37], v[162:165], v[146:149]
	v_mfma_i32_16x16x64_i8 v[110:113], v[34:37], v[170:173], v[110:113]
	v_mfma_i32_16x16x64_i8 v[118:121], v[18:21], v[170:173], v[118:121]
	v_mfma_i32_16x16x64_i8 v[54:57], v[18:21], v[178:181], v[54:57]
	v_mfma_i32_16x16x64_i8 v[30:33], v[34:37], v[178:181], v[30:33]
	v_mfma_i32_16x16x64_i8 v[58:61], v[34:37], v[186:189], v[58:61]
	v_mfma_i32_16x16x64_i8 v[94:97], v[18:21], v[186:189], v[94:97]
	v_mfma_i32_16x16x64_i8 v[150:153], v[22:25], v[166:169], v[150:153]
	v_mfma_i32_16x16x64_i8 v[146:149], v[38:41], v[166:169], v[146:149]
	v_mfma_i32_16x16x64_i8 v[110:113], v[38:41], v[174:177], v[110:113]
	v_mfma_i32_16x16x64_i8 v[118:121], v[22:25], v[174:177], v[118:121]
	v_mfma_i32_16x16x64_i8 v[54:57], v[22:25], v[182:185], v[54:57]
	v_mfma_i32_16x16x64_i8 v[30:33], v[38:41], v[182:185], v[30:33]
	v_mfma_i32_16x16x64_i8 v[58:61], v[38:41], v[190:193], v[58:61]
	v_mfma_i32_16x16x64_i8 v[94:97], v[22:25], v[190:193], v[94:97]
	v_mfma_i32_16x16x64_i8 v[142:145], v[130:133], v[162:165], v[142:145]
	v_mfma_i32_16x16x64_i8 v[138:141], v[154:157], v[162:165], v[138:141]
	v_mfma_i32_16x16x64_i8 v[98:101], v[154:157], v[170:173], v[98:101]
	v_mfma_i32_16x16x64_i8 v[102:105], v[130:133], v[170:173], v[102:105]
	v_mfma_i32_16x16x64_i8 v[42:45], v[130:133], v[178:181], v[42:45]
	v_mfma_i32_16x16x64_i8 v[26:29], v[154:157], v[178:181], v[26:29]
	v_mfma_i32_16x16x64_i8 v[62:65], v[154:157], v[186:189], v[62:65]
	v_mfma_i32_16x16x64_i8 v[78:81], v[130:133], v[186:189], v[78:81]
	v_mfma_i32_16x16x64_i8 v[142:145], v[134:137], v[166:169], v[142:145]
	v_mfma_i32_16x16x64_i8 v[138:141], v[158:161], v[166:169], v[138:141]
	v_mfma_i32_16x16x64_i8 v[98:101], v[158:161], v[174:177], v[98:101]
	v_mfma_i32_16x16x64_i8 v[102:105], v[134:137], v[174:177], v[102:105]
	v_mfma_i32_16x16x64_i8 v[42:45], v[134:137], v[182:185], v[42:45]
	v_mfma_i32_16x16x64_i8 v[26:29], v[158:161], v[182:185], v[26:29]
	v_mfma_i32_16x16x64_i8 v[62:65], v[158:161], v[190:193], v[62:65]
	v_mfma_i32_16x16x64_i8 v[78:81], v[134:137], v[190:193], v[78:81]
	s_barrier
	s_add_i32 s0, vcc_hi, s69
	s_mov_b32 m0, s0
	ds_read_b128 v[162:165], v243 offset:16384
	ds_read_b128 v[166:169], v243 offset:17408
	ds_read_b128 v[170:173], v243 offset:18432
	ds_read_b128 v[174:177], v243 offset:19456
	ds_read_b128 v[178:181], v243 offset:20480
	ds_read_b128 v[182:185], v243 offset:21504
	ds_read_b128 v[186:189], v243 offset:22528
	ds_read_b128 v[190:193], v243 offset:23552
	global_load_lds_dwordx4 v0, s[6:7]
	s_add_i32 m0, s0, 0x2000
	s_add_u32 s0, s6, 0x40000
	s_addc_u32 s1, s7, 0
	s_add_i32 s4, s4, s69
	global_load_lds_dwordx4 v214, s[6:7]
	s_mov_b32 m0, s4
	s_nop 0
	global_load_lds_dwordx4 v0, s[0:1]
	s_add_i32 m0, s4, 0x2000
	s_nop 0
	global_load_lds_dwordx4 v214, s[0:1]
	s_mov_b32 m0, s11
	s_nop 0
	global_load_lds_dwordx4 v210, s[12:13]
	s_mov_b32 m0, s71
	s_nop 0
	global_load_lds_dwordx4 v212, s[12:13]
	s_waitcnt vmcnt(8)
	s_waitcnt lgkmcnt(0)
	s_barrier
	s_waitcnt lgkmcnt(0)
	v_mfma_i32_16x16x64_i8 v[106:109], v[18:21], v[162:165], v[106:109]
	v_mfma_i32_16x16x64_i8 v[46:49], v[34:37], v[162:165], v[46:49]
	v_mfma_i32_16x16x64_i8 v[6:9], v[34:37], v[170:173], v[6:9]
	v_mfma_i32_16x16x64_i8 v[14:17], v[18:21], v[170:173], v[14:17]
	v_mfma_i32_16x16x64_i8 v[90:93], v[18:21], v[178:181], v[90:93]
	v_mfma_i32_16x16x64_i8 v[86:89], v[34:37], v[178:181], v[86:89]
	v_mfma_i32_16x16x64_i8 v[18:21], v[18:21], v[186:189], v[126:129]
	v_mfma_i32_16x16x64_i8 v[106:109], v[22:25], v[166:169], v[106:109]
	v_mfma_i32_16x16x64_i8 v[46:49], v[38:41], v[166:169], v[46:49]
	v_mfma_i32_16x16x64_i8 v[6:9], v[38:41], v[174:177], v[6:9]
	v_mfma_i32_16x16x64_i8 v[14:17], v[22:25], v[174:177], v[14:17]
	v_mfma_i32_16x16x64_i8 v[90:93], v[22:25], v[182:185], v[90:93]
	v_mfma_i32_16x16x64_i8 v[86:89], v[38:41], v[182:185], v[86:89]
	v_mfma_i32_16x16x64_i8 v[18:21], v[22:25], v[190:193], v[18:21]
	v_mfma_i32_16x16x64_i8 v[22:25], v[34:37], v[186:189], v[66:69]
	v_mfma_i32_16x16x64_i8 v[22:25], v[38:41], v[190:193], v[22:25]
	v_mfma_i32_16x16x64_i8 v[38:41], v[154:157], v[162:165], v[50:53]
	v_mfma_i32_16x16x64_i8 v[2:5], v[154:157], v[170:173], v[2:5]
	v_mfma_i32_16x16x64_i8 v[10:13], v[130:133], v[170:173], v[10:13]
	v_mfma_i32_16x16x64_i8 v[50:53], v[130:133], v[178:181], v[82:85]
	v_mfma_i32_16x16x64_i8 v[34:37], v[130:133], v[162:165], v[114:117]
	v_mfma_i32_16x16x64_i8 v[82:85], v[134:137], v[182:185], v[50:53]
	v_mfma_i32_16x16x64_i8 v[50:53], v[154:157], v[178:181], v[74:77]
	v_mfma_i32_16x16x64_i8 v[2:5], v[158:161], v[174:177], v[2:5]
	v_mfma_i32_16x16x64_i8 v[10:13], v[134:137], v[174:177], v[10:13]
	v_mfma_i32_16x16x64_i8 v[38:41], v[158:161], v[166:169], v[38:41]
	v_mfma_i32_16x16x64_i8 v[34:37], v[134:137], v[166:169], v[34:37]
	v_mfma_i32_16x16x64_i8 v[74:77], v[158:161], v[182:185], v[50:53]
	v_mfma_i32_16x16x64_i8 v[50:53], v[130:133], v[186:189], v[122:125]
	v_mfma_i32_16x16x64_i8 v[122:125], v[134:137], v[190:193], v[50:53]
	v_mfma_i32_16x16x64_i8 v[50:53], v[154:157], v[186:189], v[70:73]
	v_mfma_i32_16x16x64_i8 v[70:73], v[158:161], v[190:193], v[50:53]
	s_barrier
; #define PG8_STAGE(bufoff, gbase, voff) do { _Pragma("unroll") for (int _i = 0; _i < 2; ++_i) \
;         __builtin_amdgcn_global_load_lds((const unsigned*)((const char*)(gbase) + (voff)[_i]), (PG8_LAS unsigned*)(lds + (bufoff) + ldsw + _i * 8192), 16, 0, 0); } while (0)
; #define PG8_LDA(dst, b, h) do { _Pragma("unroll") for (int m = 0; m < 4; ++m) _Pragma("unroll") for (int k = 0; k < 2; ++k) dst[m][k] = *(const PG8_LAS bf16x8*)(lds + PG8_SA(b, h) + aoff + m * 2048 + k * 1024); } while (0)
; #define PG8_LDB(dst, b, h) do { _Pragma("unroll") for (int n = 0; n < 2; ++n) _Pragma("unroll") for (int k = 0; k < 2; ++k) dst[n][k] = *(const PG8_LAS bf16x8*)(lds + PG8_SB(b, h) + boff + n * 2048 + k * 1024); } while (0)
; #define PG8_MMA(ai, bj, At, Bt) do { __builtin_amdgcn_s_setprio(1); _Pragma("unroll") for (int m = 0; m < 4; ++m) _Pragma("unroll") for (int n = 0; n < 2; ++n) _Pragma("unroll") for (int k = 0; k < 2; ++k) \
;         acc[ai][bj][m][n] = mma16<Epi::I8>(Bt[n][k], At[m][k], acc[ai][bj][m][n]); __builtin_amdgcn_s_setprio(0); } while (0)
; #define PG8_WAIT_V(n) asm volatile("s_waitcnt vmcnt(" #n ")" ::: "memory")
; #define PG8_WAIT_L(n) asm volatile("s_waitcnt lgkmcnt(" #n ")" ::: "memory")
; #define PG8_BAR __builtin_amdgcn_s_barrier()
; #define PG8_SCHED __builtin_amdgcn_sched_barrier(0)
; template <class Epi, class Sched, bool ALIGN_EPI = false, bool SP2 = false>
; __device__ __forceinline__ void gemm_phase(PG8_LAS unsigned char* lds, const Gemm g, const Sched& S, const Epi& E) {
;     ...
;         for (int t = 0; t < nt; t += 2) {
;     ...
;             PG8_LDB(B0, 1, 0); PG8_LDB(B1, 1, 1); PG8_SCHED; PG8_LDA(At, 1, 0); PG8_STAGE(PG8_SA(0, 1), a2 + hstep, voffA);
;             PG8_WAIT_V(8); PG8_WAIT_L(0); PG8_BAR; PG8_MMA(0, 0, At, B0); PG8_MMA(0, 1, At, B1); PG8_BAR; PG8_SCHED;
;             PG8_LDA(At, 1, 1); PG8_STAGE(PG8_SB(1, 0), b3, voffB); PG8_STAGE(PG8_SB(1, 1), b3 + hstep, voffB); PG8_STAGE(PG8_SA(1, 0), a3, voffA);
;             PG8_WAIT_V(8); PG8_WAIT_L(0); PG8_BAR; PG8_MMA(1, 0, At, B0); PG8_MMA(1, 1, At, B1); PG8_BAR; PG8_SCHED;
	s_add_i32 s4, 0, 0x18000
	v_add_u32_e32 v126, s4, v242
	s_add_i32 s5, 0, 0x1c000
	ds_read_b128 v[50:53], v126
	ds_read_b128 v[66:69], v126 offset:1024
	ds_read_b128 v[114:117], v126 offset:2048
	ds_read_b128 v[130:133], v126 offset:3072
	v_add_u32_e32 v126, s5, v242
	ds_read_b128 v[134:137], v126
	ds_read_b128 v[154:157], v126 offset:1024
	ds_read_b128 v[158:161], v126 offset:2048
	ds_read_b128 v[162:165], v126 offset:3072
	s_add_u32 s0, s12, 0x40000
	s_addc_u32 s1, s13, 0
	s_mov_b32 m0, s80
	ds_read_b128 v[126:129], v243 offset:32768
	ds_read_b128 v[166:169], v243 offset:33792
	ds_read_b128 v[170:173], v243 offset:34816
	ds_read_b128 v[174:177], v243 offset:35840
	ds_read_b128 v[178:181], v243 offset:36864
	ds_read_b128 v[182:185], v243 offset:37888
	ds_read_b128 v[186:189], v243 offset:38912
	ds_read_b128 v[190:193], v243 offset:39936
	global_load_lds_dwordx4 v210, s[0:1]
	s_mov_b32 m0, s81
	s_nop 0
	global_load_lds_dwordx4 v212, s[0:1]
	s_waitcnt vmcnt(8)
	s_waitcnt lgkmcnt(0)
	s_barrier
	s_waitcnt lgkmcnt(0)
	v_mfma_i32_16x16x64_i8 v[150:153], v[50:53], v[126:129], v[150:153]
	v_mfma_i32_16x16x64_i8 v[146:149], v[114:117], v[126:129], v[146:149]
	v_mfma_i32_16x16x64_i8 v[110:113], v[114:117], v[170:173], v[110:113]
	v_mfma_i32_16x16x64_i8 v[118:121], v[50:53], v[170:173], v[118:121]
	v_mfma_i32_16x16x64_i8 v[54:57], v[50:53], v[178:181], v[54:57]
	v_mfma_i32_16x16x64_i8 v[30:33], v[114:117], v[178:181], v[30:33]
	v_mfma_i32_16x16x64_i8 v[58:61], v[114:117], v[186:189], v[58:61]
	v_mfma_i32_16x16x64_i8 v[94:97], v[50:53], v[186:189], v[94:97]
	v_mfma_i32_16x16x64_i8 v[150:153], v[66:69], v[166:169], v[150:153]
	v_mfma_i32_16x16x64_i8 v[146:149], v[130:133], v[166:169], v[146:149]
	v_mfma_i32_16x16x64_i8 v[110:113], v[130:133], v[174:177], v[110:113]
	v_mfma_i32_16x16x64_i8 v[118:121], v[66:69], v[174:177], v[118:121]
	v_mfma_i32_16x16x64_i8 v[54:57], v[66:69], v[182:185], v[54:57]
	v_mfma_i32_16x16x64_i8 v[30:33], v[130:133], v[182:185], v[30:33]
	v_mfma_i32_16x16x64_i8 v[58:61], v[130:133], v[190:193], v[58:61]
	v_mfma_i32_16x16x64_i8 v[94:97], v[66:69], v[190:193], v[94:97]
	v_mfma_i32_16x16x64_i8 v[142:145], v[134:137], v[126:129], v[142:145]
	v_mfma_i32_16x16x64_i8 v[126:129], v[158:161], v[126:129], v[138:141]
	v_mfma_i32_16x16x64_i8 v[98:101], v[158:161], v[170:173], v[98:101]
	v_mfma_i32_16x16x64_i8 v[102:105], v[134:137], v[170:173], v[102:105]
	v_mfma_i32_16x16x64_i8 v[42:45], v[134:137], v[178:181], v[42:45]
	v_mfma_i32_16x16x64_i8 v[26:29], v[158:161], v[178:181], v[26:29]
	v_mfma_i32_16x16x64_i8 v[62:65], v[158:161], v[186:189], v[62:65]
	v_mfma_i32_16x16x64_i8 v[78:81], v[134:137], v[186:189], v[78:81]
	v_mfma_i32_16x16x64_i8 v[142:145], v[154:157], v[166:169], v[142:145]
	v_mfma_i32_16x16x64_i8 v[138:141], v[162:165], v[166:169], v[126:129]
	v_mfma_i32_16x16x64_i8 v[98:101], v[162:165], v[174:177], v[98:101]
	v_mfma_i32_16x16x64_i8 v[102:105], v[154:157], v[174:177], v[102:105]
	v_mfma_i32_16x16x64_i8 v[42:45], v[154:157], v[182:185], v[42:45]
	v_mfma_i32_16x16x64_i8 v[26:29], v[162:165], v[182:185], v[26:29]
	v_mfma_i32_16x16x64_i8 v[62:65], v[162:165], v[190:193], v[62:65]
	v_mfma_i32_16x16x64_i8 v[78:81], v[154:157], v[190:193], v[78:81]
	s_barrier
	s_add_u32 s98, s6, 0x80
	s_addc_u32 s99, s7, 0
	s_add_u32 s100, s12, 0x80
	s_addc_u32 s101, s13, 0
	s_add_i32 s0, s4, s69
	s_mov_b32 m0, s0
	ds_read_b128 v[166:169], v243 offset:49152
	ds_read_b128 v[170:173], v243 offset:50176
	ds_read_b128 v[174:177], v243 offset:51200
	ds_read_b128 v[178:181], v243 offset:52224
	ds_read_b128 v[182:185], v243 offset:53248
	ds_read_b128 v[186:189], v243 offset:54272
	ds_read_b128 v[190:193], v243 offset:55296
	ds_read_b128 v[194:197], v243 offset:56320
	global_load_lds_dwordx4 v0, s[98:99]
	s_add_i32 m0, s0, 0x2000
	s_add_u32 s0, s6, 0x40080
	s_addc_u32 s1, s7, 0
	s_add_i32 s4, s5, s69
	global_load_lds_dwordx4 v214, s[98:99]
	s_mov_b32 m0, s4
	s_nop 0
	global_load_lds_dwordx4 v0, s[0:1]
	s_add_i32 m0, s4, 0x2000
	s_nop 0
	global_load_lds_dwordx4 v214, s[0:1]
	s_mov_b32 m0, s84
	s_nop 0
	global_load_lds_dwordx4 v210, s[100:101]
	s_mov_b32 m0, s85
	s_nop 0
	global_load_lds_dwordx4 v212, s[100:101]
	s_waitcnt vmcnt(8)
	s_waitcnt lgkmcnt(0)
	s_barrier
	s_waitcnt lgkmcnt(0)
	v_mfma_i32_16x16x64_i8 v[18:21], v[50:53], v[190:193], v[18:21]
	v_mfma_i32_16x16x64_i8 v[106:109], v[50:53], v[166:169], v[106:109]
	v_mfma_i32_16x16x64_i8 v[46:49], v[114:117], v[166:169], v[46:49]
	v_mfma_i32_16x16x64_i8 v[6:9], v[114:117], v[174:177], v[6:9]
	v_mfma_i32_16x16x64_i8 v[14:17], v[50:53], v[174:177], v[14:17]
	v_mfma_i32_16x16x64_i8 v[90:93], v[50:53], v[182:185], v[90:93]
	v_mfma_i32_16x16x64_i8 v[86:89], v[114:117], v[182:185], v[86:89]
	v_mfma_i32_16x16x64_i8 v[126:129], v[66:69], v[194:197], v[18:21]
	v_mfma_i32_16x16x64_i8 v[106:109], v[66:69], v[170:173], v[106:109]
	v_mfma_i32_16x16x64_i8 v[46:49], v[130:133], v[170:173], v[46:49]
	v_mfma_i32_16x16x64_i8 v[6:9], v[130:133], v[178:181], v[6:9]
	v_mfma_i32_16x16x64_i8 v[14:17], v[66:69], v[178:181], v[14:17]
	v_mfma_i32_16x16x64_i8 v[90:93], v[66:69], v[186:189], v[90:93]
	v_mfma_i32_16x16x64_i8 v[86:89], v[130:133], v[186:189], v[86:89]
	v_mfma_i32_16x16x64_i8 v[18:21], v[114:117], v[190:193], v[22:25]
	v_mfma_i32_16x16x64_i8 v[66:69], v[130:133], v[194:197], v[18:21]
	v_mfma_i32_16x16x64_i8 v[18:21], v[134:137], v[166:169], v[34:37]
	v_mfma_i32_16x16x64_i8 v[10:13], v[134:137], v[174:177], v[10:13]
	v_mfma_i32_16x16x64_i8 v[2:5], v[158:161], v[174:177], v[2:5]
	v_mfma_i32_16x16x64_i8 v[114:117], v[154:157], v[170:173], v[18:21]
	v_mfma_i32_16x16x64_i8 v[18:21], v[158:161], v[166:169], v[38:41]
	v_mfma_i32_16x16x64_i8 v[50:53], v[162:165], v[170:173], v[18:21]
	v_mfma_i32_16x16x64_i8 v[18:21], v[134:137], v[182:185], v[82:85]
	v_mfma_i32_16x16x64_i8 v[10:13], v[154:157], v[178:181], v[10:13]
	v_mfma_i32_16x16x64_i8 v[2:5], v[162:165], v[178:181], v[2:5]
	v_mfma_i32_16x16x64_i8 v[82:85], v[154:157], v[186:189], v[18:21]
	v_mfma_i32_16x16x64_i8 v[18:21], v[158:161], v[182:185], v[74:77]
	v_mfma_i32_16x16x64_i8 v[74:77], v[162:165], v[186:189], v[18:21]
	v_mfma_i32_16x16x64_i8 v[18:21], v[134:137], v[190:193], v[122:125]
	v_mfma_i32_16x16x64_i8 v[122:125], v[154:157], v[194:197], v[18:21]
	v_mfma_i32_16x16x64_i8 v[18:21], v[158:161], v[190:193], v[70:73]
	v_mfma_i32_16x16x64_i8 v[70:73], v[162:165], v[194:197], v[18:21]
	s_barrier
	s_add_i32 vcc_lo, vcc_lo, 2
	s_add_u32 s96, s96, 0x100
	s_addc_u32 s97, s97, 0
	s_cmp_gt_u32 vcc_lo, 13
	s_mov_b64 s[0:1], s[8:9]
	s_cbranch_scc0 .LBB0_80
